# static s_setprio 1 for the map-1 (younger) attention waves during their key loop, matched placement
# speedup vs baseline: 1.0004x; 1.0004x over previous
.LBB0_621:
	s_nop 10
	v_max_f32_e32 v32, v1, v1
	v_max_f32_e32 v33, v17, v17
	v_max_f32_e32 v32, v33, v32
	v_max_f32_e32 v33, v2, v2
	v_max_f32_e32 v34, v18, v18
	v_max_f32_e32 v33, v34, v33
	v_max_f32_e32 v34, v3, v3
	v_max_f32_e32 v35, v19, v19
	v_max3_f32 v32, v16, v0, v32
	v_max_f32_e32 v34, v35, v34
	v_max3_f32 v32, v32, v33, v34
	v_max_f32_e32 v33, v4, v4
	v_max_f32_e32 v34, v20, v20
	v_max_f32_e32 v33, v34, v33
	v_max_f32_e32 v34, v5, v5
	v_max_f32_e32 v35, v21, v21
	v_max_f32_e32 v34, v35, v34
	v_max3_f32 v32, v32, v33, v34
	v_max_f32_e32 v33, v6, v6
	v_max_f32_e32 v34, v22, v22
	v_max_f32_e32 v33, v34, v33
	v_max_f32_e32 v34, v7, v7
	v_max_f32_e32 v35, v23, v23
	v_max_f32_e32 v34, v35, v34
	v_max3_f32 v32, v32, v33, v34
	v_max_f32_e32 v33, v8, v8
	v_max_f32_e32 v34, v24, v24
	v_max_f32_e32 v33, v34, v33
	v_max_f32_e32 v34, v9, v9
	v_max_f32_e32 v35, v25, v25
	v_max_f32_e32 v34, v35, v34
	v_max3_f32 v32, v32, v33, v34
	v_max_f32_e32 v33, v10, v10
	v_max_f32_e32 v34, v26, v26
	v_max_f32_e32 v33, v34, v33
	v_max_f32_e32 v34, v11, v11
	v_max_f32_e32 v35, v27, v27
	v_max_f32_e32 v34, v35, v34
	v_max3_f32 v32, v32, v33, v34
	v_max_f32_e32 v33, v12, v12
	v_max_f32_e32 v34, v28, v28
	v_max_f32_e32 v33, v34, v33
	v_max_f32_e32 v34, v13, v13
	v_max_f32_e32 v35, v29, v29
	v_max_f32_e32 v34, v35, v34
	v_max3_f32 v32, v32, v33, v34
	v_max_f32_e32 v33, v14, v14
	v_max_f32_e32 v34, v30, v30
	v_max_f32_e32 v33, v34, v33
	v_max_f32_e32 v34, v15, v15
	v_max_f32_e32 v35, v31, v31
	v_max_f32_e32 v34, v35, v34
	v_max3_f32 v32, v32, v33, v34
	v_mov_b32_e32 v33, v32
	s_nop 1
	v_permlane32_swap_b32_e32 v32, v33
	v_max_f32_e32 v33, v33, v33
	v_max_f32_e32 v32, v32, v32
	v_max_f32_e32 v64, v32, v33
	v_sub_f32_e32 v32, v0, v64
	v_sub_f32_e32 v0, v16, v64
	v_sub_f32_e32 v33, v1, v64
	v_sub_f32_e32 v1, v17, v64
	v_exp_f32_e32 v0, v0
	v_sub_f32_e32 v34, v2, v64
	v_sub_f32_e32 v2, v18, v64
	v_exp_f32_e32 v1, v1
	v_sub_f32_e32 v35, v3, v64
	v_sub_f32_e32 v3, v19, v64
	v_exp_f32_e32 v2, v2
	v_sub_f32_e32 v36, v4, v64
	v_sub_f32_e32 v4, v20, v64
	v_exp_f32_e32 v3, v3
	v_sub_f32_e32 v37, v5, v64
	v_sub_f32_e32 v5, v21, v64
	v_add_f32_e32 v16, 0, v0
	v_exp_f32_e32 v4, v4
	v_sub_f32_e32 v38, v6, v64
	v_sub_f32_e32 v6, v22, v64
	v_add_f32_e32 v16, v1, v16
	v_exp_f32_e32 v5, v5
	v_sub_f32_e32 v39, v7, v64
	v_sub_f32_e32 v7, v23, v64
	v_add_f32_e32 v16, v2, v16
	v_exp_f32_e32 v6, v6
	v_sub_f32_e32 v65, v8, v64
	v_sub_f32_e32 v8, v24, v64
	v_add_f32_e32 v16, v3, v16
	v_exp_f32_e32 v7, v7
	v_sub_f32_e32 v98, v9, v64
	v_sub_f32_e32 v9, v25, v64
	v_add_f32_e32 v16, v4, v16
	v_exp_f32_e32 v8, v8
	v_sub_f32_e32 v99, v10, v64
	v_sub_f32_e32 v10, v26, v64
	v_add_f32_e32 v16, v5, v16
	v_exp_f32_e32 v9, v9
	v_sub_f32_e32 v100, v11, v64
	v_sub_f32_e32 v11, v27, v64
	v_add_f32_e32 v16, v6, v16
	v_exp_f32_e32 v10, v10
	v_sub_f32_e32 v101, v12, v64
	v_sub_f32_e32 v12, v28, v64
	v_add_f32_e32 v16, v7, v16
	v_exp_f32_e32 v11, v11
	v_sub_f32_e32 v102, v13, v64
	v_sub_f32_e32 v13, v29, v64
	v_add_f32_e32 v16, v8, v16
	v_exp_f32_e32 v12, v12
	v_sub_f32_e32 v103, v14, v64
	v_sub_f32_e32 v14, v30, v64
	v_add_f32_e32 v16, v9, v16
	v_exp_f32_e32 v13, v13
	v_sub_f32_e32 v104, v15, v64
	v_sub_f32_e32 v15, v31, v64
	v_add_f32_e32 v16, v10, v16
	v_exp_f32_e32 v14, v14
	v_add_f32_e32 v16, v11, v16
	v_exp_f32_e32 v15, v15
	v_add_f32_e32 v16, v12, v16
	v_add_f32_e32 v16, v13, v16
	v_mul_u32_u24_e32 v143, 0x90, v140
	v_and_b32_e32 v163, 32, v141
	v_add_f32_e32 v16, v14, v16
	v_add_f32_e32 v16, v15, v16
	s_waitcnt vmcnt(5) lgkmcnt(0)
	s_barrier
	v_add3_u32 v105, 0, v143, v163
	v_add_f32_e32 v107, 0, v16
	v_cvt_pk_bf16_f32 v16, v0, v1
	v_cvt_pk_bf16_f32 v17, v2, v3
	v_cvt_pk_bf16_f32 v18, v4, v5
	v_cvt_pk_bf16_f32 v19, v6, v7
	ds_read_b128 v[0:3], v105 offset:18432
	ds_read_b128 v[20:23], v105 offset:18448
	ds_read_b128 v[4:7], v105 offset:23040
	ds_read_b128 v[24:27], v105 offset:23056
	v_cvt_pk_bf16_f32 v66, v8, v9
	v_cvt_pk_bf16_f32 v67, v10, v11
	v_cvt_pk_bf16_f32 v68, v12, v13
	v_cvt_pk_bf16_f32 v69, v14, v15
	ds_read_b128 v[28:31], v105 offset:27648
	ds_read_b128 v[70:73], v105 offset:27664
	ds_read_b128 v[74:77], v105 offset:32256
	ds_read_b128 v[78:81], v105 offset:32272
	s_waitcnt lgkmcnt(0)
	v_mfma_f32_32x32x16_bf16 v[48:63], v[0:3], v[16:19], 0
	v_exp_f32_e32 v106, v32
	v_exp_f32_e32 v108, v33
	v_exp_f32_e32 v109, v34
	v_exp_f32_e32 v110, v35
	v_mfma_f32_32x32x16_bf16 v[0:15], v[4:7], v[16:19], 0
	v_mfma_f32_32x32x16_bf16 v[48:63], v[20:23], v[66:69], v[48:63]
	v_exp_f32_e32 v111, v36
	v_exp_f32_e32 v128, v37
	v_exp_f32_e32 v129, v38
	v_exp_f32_e32 v130, v39
	v_mfma_f32_32x32x16_bf16 v[0:15], v[24:27], v[66:69], v[0:15]
	ds_read_b128 v[82:85], v105 offset:18496
	ds_read_b128 v[86:89], v105 offset:18512
	ds_read_b128 v[90:93], v105 offset:23104
	ds_read_b128 v[94:97], v105 offset:23120
	v_mfma_f32_32x32x16_bf16 v[32:47], v[28:31], v[16:19], 0
	v_exp_f32_e32 v65, v65
	v_exp_f32_e32 v131, v98
	v_exp_f32_e32 v132, v99
	v_exp_f32_e32 v133, v100
	v_mfma_f32_32x32x16_bf16 v[16:31], v[74:77], v[16:19], 0
	v_mfma_f32_32x32x16_bf16 v[32:47], v[70:73], v[66:69], v[32:47]
	v_exp_f32_e32 v134, v101
	v_exp_f32_e32 v135, v102
	v_exp_f32_e32 v136, v103
	v_exp_f32_e32 v137, v104
	v_cvt_pk_bf16_f32 v70, v65, v131
	v_cvt_pk_bf16_f32 v71, v132, v133
	v_cvt_pk_bf16_f32 v72, v134, v135
	v_mfma_f32_32x32x16_bf16 v[16:31], v[78:81], v[66:69], v[16:31]
	v_cvt_pk_bf16_f32 v66, v106, v108
	v_cvt_pk_bf16_f32 v67, v109, v110
	v_cvt_pk_bf16_f32 v68, v111, v128
	v_cvt_pk_bf16_f32 v69, v129, v130
	v_cvt_pk_bf16_f32 v73, v136, v137
	ds_read_b128 v[74:77], v105 offset:27712
	ds_read_b128 v[78:81], v105 offset:27728
	ds_read_b128 v[98:101], v105 offset:32320
	ds_read_b128 v[102:105], v105 offset:32336
	s_waitcnt lgkmcnt(0)
	v_mfma_f32_32x32x16_bf16 v[48:63], v[82:85], v[66:69], v[48:63]
	v_mfma_f32_32x32x16_bf16 v[0:15], v[90:93], v[66:69], v[0:15]
	v_mfma_f32_32x32x16_bf16 v[48:63], v[86:89], v[70:73], v[48:63]
	v_mfma_f32_32x32x16_bf16 v[0:15], v[94:97], v[70:73], v[0:15]
	v_mfma_f32_32x32x16_bf16 v[32:47], v[74:77], v[66:69], v[32:47]
	v_mfma_f32_32x32x16_bf16 v[16:31], v[98:101], v[66:69], v[16:31]
	v_mfma_f32_32x32x16_bf16 v[32:47], v[78:81], v[70:73], v[32:47]
	v_mfma_f32_32x32x16_bf16 v[16:31], v[102:105], v[70:73], v[16:31]
	v_add_f32_e32 v66, 0, v106
	v_add_f32_e32 v66, v108, v66
	v_add_f32_e32 v66, v109, v66
	v_add_f32_e32 v66, v110, v66
	v_add_f32_e32 v66, v111, v66
	v_add_f32_e32 v66, v128, v66
	v_add_f32_e32 v66, v129, v66
	v_add_f32_e32 v66, v130, v66
	v_add_f32_e32 v65, v65, v66
	v_add_f32_e32 v65, v131, v65
	v_add_f32_e32 v65, v132, v65
	v_add_f32_e32 v65, v133, v65
	v_add_f32_e32 v65, v134, v65
	v_add_f32_e32 v65, v135, v65
	v_add_f32_e32 v65, v136, v65
	v_add_f32_e32 v65, v137, v65
	v_mov_b32_e32 v106, v177
	s_add_i32 s4, s20, s88
	s_waitcnt lgkmcnt(0)
	s_barrier
	v_pk_add_f32 v[156:157], v[64:65], v[106:107]
	v_add_u32_e32 v65, s4, v140
	v_sub_f32_e32 v64, v142, v156
	v_sub_u32_e32 v65, v146, v65
	v_add_u32_e32 v164, 64, v65
	s_mov_b32 s87, 0
	s_sub_i32 s91, 0, s4
	s_mov_b32 s8, 1
	s_mov_b32 s9, 0x9000
	s_mov_b64 s[46:47], s[10:11]
	s_mov_b64 s[40:41], s[76:77]
	s_mov_b32 s56, 0
	v_mov_b32_e32 v65, v64
	v_mov_b32_e32 v66, v64
	v_mov_b32_e32 v67, v64
	v_mov_b32_e32 v68, v64
	v_mov_b32_e32 v69, v64
	v_mov_b32_e32 v70, v64
	v_mov_b32_e32 v71, v64
	v_mov_b32_e32 v72, v64
	v_mov_b32_e32 v73, v64
	v_mov_b32_e32 v74, v64
	v_mov_b32_e32 v75, v64
	v_mov_b32_e32 v76, v64
	v_mov_b32_e32 v77, v64
	v_mov_b32_e32 v78, v64
	v_mov_b32_e32 v79, v64
	s_add_u32 vcc_lo, s46, 0xffffff80
	s_addc_u32 vcc_hi, s47, -1
	s_mov_b32 s16, 0x60000
	s_and_b64 s[4:5], s[52:53], exec
	s_cselect_b32 s17, s41, vcc_hi
	s_cselect_b32 s80, s40, vcc_lo
	s_cselect_b32 s81, 0x80, s16
	s_and_b64 s[4:5], s[48:49], exec
	s_cselect_b32 s17, s47, s17
	s_cselect_b32 s80, s46, s80
	s_cselect_b32 s81, s16, s81
	s_and_b64 s[4:5], s[36:37], exec
	s_cselect_b32 s5, vcc_hi, s17
	s_cselect_b32 s4, vcc_lo, s80
	s_cselect_b32 s81, s16, s81
	v_lshl_add_u64 v[240:241], s[4:5], 0, v[176:177]
	v_mov_b32_e32 v200, s81
	v_mov_b32_e32 v201, 0
	s_and_b64 s[4:5], s[28:29], exec
	s_cselect_b32 s17, s41, vcc_hi
	s_cselect_b32 s80, s40, vcc_lo
	s_cselect_b32 s81, 0x80, s16
	s_and_b64 s[4:5], s[66:67], exec
	s_cselect_b32 s17, s47, s17
	s_cselect_b32 s80, s46, s80
	s_cselect_b32 s81, s16, s81
	s_and_b64 s[4:5], s[50:51], exec
	s_cselect_b32 s5, vcc_hi, s17
	s_cselect_b32 s4, vcc_lo, s80
	s_cselect_b32 s81, s16, s81
	v_lshl_add_u64 v[242:243], s[4:5], 0, v[148:149]
	v_mov_b32_e32 v202, s81
	v_mov_b32_e32 v203, 0
	s_and_b64 s[4:5], s[60:61], exec
	s_cselect_b32 s17, s41, vcc_hi
	s_cselect_b32 s80, s40, vcc_lo
	s_cselect_b32 s81, 0x80, s16
	s_and_b64 s[4:5], s[38:39], exec
	s_cselect_b32 s17, s47, s17
	s_cselect_b32 s80, s46, s80
	s_cselect_b32 s81, s16, s81
	s_and_b64 s[4:5], s[62:63], exec
	s_cselect_b32 s5, vcc_hi, s17
	s_cselect_b32 s4, vcc_lo, s80
	s_cselect_b32 s81, s16, s81
	v_lshl_add_u64 v[244:245], s[4:5], 0, v[150:151]
	v_mov_b32_e32 v204, s81
	v_mov_b32_e32 v205, 0
	s_and_b64 s[4:5], s[6:7], exec
	s_cselect_b32 s17, s41, vcc_hi
	s_cselect_b32 s80, s40, vcc_lo
	s_cselect_b32 s81, 0x80, s16
	s_and_b64 s[4:5], s[12:13], exec
	s_cselect_b32 s17, s47, s17
	s_cselect_b32 s80, s46, s80
	s_cselect_b32 s81, s16, s81
	s_and_b64 s[4:5], s[22:23], exec
	s_cselect_b32 s5, vcc_hi, s17
	s_cselect_b32 s4, vcc_lo, s80
	s_cselect_b32 s81, s16, s81
	v_lshl_add_u64 v[246:247], s[4:5], 0, v[152:153]
	v_mov_b32_e32 v206, s81
	v_mov_b32_e32 v207, 0
	s_and_b64 s[4:5], s[14:15], exec
	s_cselect_b32 s17, s41, vcc_hi
	s_cselect_b32 s80, s40, vcc_lo
	s_cselect_b32 s81, 0x80, s16
	s_and_b64 s[4:5], s[0:1], exec
	s_cselect_b32 s17, s47, s17
	s_cselect_b32 s80, s46, s80
	s_cselect_b32 s81, s16, s81
	s_and_b64 s[4:5], s[68:69], exec
	s_cselect_b32 s5, vcc_hi, s17
	s_cselect_b32 s4, vcc_lo, s80
	s_cselect_b32 s81, s16, s81
	v_lshl_add_u64 v[248:249], s[4:5], 0, v[154:155]
	v_mov_b32_e32 v208, s81
	v_mov_b32_e32 v209, 0
	s_mov_b32 s32, 3
	s_setprio 1
	s_branch .LBB0_623

.Lv1p_flush:
	s_setprio 0
	v_mfma_f32_32x32x16_bf16 v[32:47], v[96:99], v[88:91], v[32:47]
	v_mfma_f32_32x32x16_bf16 v[16:31], v[128:131], v[88:91], v[16:31]
	v_mfma_f32_32x32x16_bf16 v[32:47], v[100:103], v[92:95], v[32:47]
	v_mfma_f32_32x32x16_bf16 v[16:31], v[132:135], v[92:95], v[16:31]

.LBB0_682:
	s_nop 10
	v_max_f32_e32 v32, v1, v1
	v_max_f32_e32 v33, v17, v17
	v_max_f32_e32 v32, v33, v32
	v_max_f32_e32 v33, v2, v2
	v_max_f32_e32 v34, v18, v18
	v_max_f32_e32 v33, v34, v33
	v_max_f32_e32 v34, v3, v3
	v_max_f32_e32 v35, v19, v19
	v_max3_f32 v32, v16, v0, v32
	v_max_f32_e32 v34, v35, v34
	v_max3_f32 v32, v32, v33, v34
	v_max_f32_e32 v33, v4, v4
	v_max_f32_e32 v34, v20, v20
	v_max_f32_e32 v33, v34, v33
	v_max_f32_e32 v34, v5, v5
	v_max_f32_e32 v35, v21, v21
	v_max_f32_e32 v34, v35, v34
	v_max3_f32 v32, v32, v33, v34
	v_max_f32_e32 v33, v6, v6
	v_max_f32_e32 v34, v22, v22
	v_max_f32_e32 v33, v34, v33
	v_max_f32_e32 v34, v7, v7
	v_max_f32_e32 v35, v23, v23
	v_max_f32_e32 v34, v35, v34
	v_max3_f32 v32, v32, v33, v34
	v_max_f32_e32 v33, v8, v8
	v_max_f32_e32 v34, v24, v24
	v_max_f32_e32 v33, v34, v33
	v_max_f32_e32 v34, v9, v9
	v_max_f32_e32 v35, v25, v25
	v_max_f32_e32 v34, v35, v34
	v_max3_f32 v32, v32, v33, v34
	v_max_f32_e32 v33, v10, v10
	v_max_f32_e32 v34, v26, v26
	v_max_f32_e32 v33, v34, v33
	v_max_f32_e32 v34, v11, v11
	v_max_f32_e32 v35, v27, v27
	v_max_f32_e32 v34, v35, v34
	v_max3_f32 v32, v32, v33, v34
	v_max_f32_e32 v33, v12, v12
	v_max_f32_e32 v34, v28, v28
	v_max_f32_e32 v33, v34, v33
	v_max_f32_e32 v34, v13, v13
	v_max_f32_e32 v35, v29, v29
	v_max_f32_e32 v34, v35, v34
	v_max3_f32 v32, v32, v33, v34
	v_max_f32_e32 v33, v14, v14
	v_max_f32_e32 v34, v30, v30
	v_max_f32_e32 v33, v34, v33
	v_max_f32_e32 v34, v15, v15
	v_max_f32_e32 v35, v31, v31
	v_max_f32_e32 v34, v35, v34
	v_max3_f32 v32, v32, v33, v34
	v_mov_b32_e32 v33, v32
	s_nop 1
	v_permlane32_swap_b32_e32 v32, v33
	v_max_f32_e32 v33, v33, v33
	v_max_f32_e32 v32, v32, v32
	v_max_f32_e32 v64, v32, v33
	v_sub_f32_e32 v32, v0, v64
	v_sub_f32_e32 v0, v16, v64
	v_sub_f32_e32 v33, v1, v64
	v_sub_f32_e32 v1, v17, v64
	v_exp_f32_e32 v0, v0
	v_sub_f32_e32 v34, v2, v64
	v_sub_f32_e32 v2, v18, v64
	v_exp_f32_e32 v1, v1
	v_sub_f32_e32 v35, v3, v64
	v_sub_f32_e32 v3, v19, v64
	v_exp_f32_e32 v2, v2
	v_sub_f32_e32 v36, v4, v64
	v_sub_f32_e32 v4, v20, v64
	v_exp_f32_e32 v3, v3
	v_sub_f32_e32 v37, v5, v64
	v_sub_f32_e32 v5, v21, v64
	v_add_f32_e32 v16, 0, v0
	v_exp_f32_e32 v4, v4
	v_sub_f32_e32 v38, v6, v64
	v_sub_f32_e32 v6, v22, v64
	v_add_f32_e32 v16, v1, v16
	v_exp_f32_e32 v5, v5
	v_sub_f32_e32 v39, v7, v64
	v_sub_f32_e32 v7, v23, v64
	v_add_f32_e32 v16, v2, v16
	v_exp_f32_e32 v6, v6
	v_sub_f32_e32 v65, v8, v64
	v_sub_f32_e32 v8, v24, v64
	v_add_f32_e32 v16, v3, v16
	v_exp_f32_e32 v7, v7
	v_sub_f32_e32 v98, v9, v64
	v_sub_f32_e32 v9, v25, v64
	v_add_f32_e32 v16, v4, v16
	v_exp_f32_e32 v8, v8
	v_sub_f32_e32 v99, v10, v64
	v_sub_f32_e32 v10, v26, v64
	v_add_f32_e32 v16, v5, v16
	v_exp_f32_e32 v9, v9
	v_sub_f32_e32 v100, v11, v64
	v_sub_f32_e32 v11, v27, v64
	v_add_f32_e32 v16, v6, v16
	v_exp_f32_e32 v10, v10
	v_sub_f32_e32 v101, v12, v64
	v_sub_f32_e32 v12, v28, v64
	v_add_f32_e32 v16, v7, v16
	v_exp_f32_e32 v11, v11
	v_sub_f32_e32 v102, v13, v64
	v_sub_f32_e32 v13, v29, v64
	v_add_f32_e32 v16, v8, v16
	v_exp_f32_e32 v12, v12
	v_sub_f32_e32 v103, v14, v64
	v_sub_f32_e32 v14, v30, v64
	v_add_f32_e32 v16, v9, v16
	v_exp_f32_e32 v13, v13
	v_sub_f32_e32 v104, v15, v64
	v_sub_f32_e32 v15, v31, v64
	v_add_f32_e32 v16, v10, v16
	v_exp_f32_e32 v14, v14
	v_add_f32_e32 v16, v11, v16
	v_exp_f32_e32 v15, v15
	v_add_f32_e32 v16, v12, v16
	v_add_f32_e32 v16, v13, v16
	v_mul_u32_u24_e32 v143, 0x90, v140
	v_and_b32_e32 v163, 32, v141
	v_add_f32_e32 v16, v14, v16
	v_add_f32_e32 v16, v15, v16
	s_waitcnt vmcnt(5) lgkmcnt(0)
	s_barrier
	v_add3_u32 v105, 0, v143, v163
	v_add_f32_e32 v107, 0, v16
	v_cvt_pk_bf16_f32 v16, v0, v1
	v_cvt_pk_bf16_f32 v17, v2, v3
	v_cvt_pk_bf16_f32 v18, v4, v5
	v_cvt_pk_bf16_f32 v19, v6, v7
	ds_read_b128 v[0:3], v105 offset:18432
	ds_read_b128 v[20:23], v105 offset:18448
	ds_read_b128 v[4:7], v105 offset:23040
	ds_read_b128 v[24:27], v105 offset:23056
	v_cvt_pk_bf16_f32 v66, v8, v9
	v_cvt_pk_bf16_f32 v67, v10, v11
	v_cvt_pk_bf16_f32 v68, v12, v13
	v_cvt_pk_bf16_f32 v69, v14, v15
	ds_read_b128 v[28:31], v105 offset:27648
	ds_read_b128 v[70:73], v105 offset:27664
	ds_read_b128 v[74:77], v105 offset:32256
	ds_read_b128 v[78:81], v105 offset:32272
	s_waitcnt lgkmcnt(0)
	v_mfma_f32_32x32x16_bf16 v[48:63], v[0:3], v[16:19], 0
	v_exp_f32_e32 v106, v32
	v_exp_f32_e32 v108, v33
	v_exp_f32_e32 v109, v34
	v_exp_f32_e32 v110, v35
	v_mfma_f32_32x32x16_bf16 v[0:15], v[4:7], v[16:19], 0
	v_mfma_f32_32x32x16_bf16 v[48:63], v[20:23], v[66:69], v[48:63]
	v_exp_f32_e32 v111, v36
	v_exp_f32_e32 v128, v37
	v_exp_f32_e32 v129, v38
	v_exp_f32_e32 v130, v39
	v_mfma_f32_32x32x16_bf16 v[0:15], v[24:27], v[66:69], v[0:15]
	ds_read_b128 v[82:85], v105 offset:18496
	ds_read_b128 v[86:89], v105 offset:18512
	ds_read_b128 v[90:93], v105 offset:23104
	ds_read_b128 v[94:97], v105 offset:23120
	v_mfma_f32_32x32x16_bf16 v[32:47], v[28:31], v[16:19], 0
	v_exp_f32_e32 v65, v65
	v_exp_f32_e32 v131, v98
	v_exp_f32_e32 v132, v99
	v_exp_f32_e32 v133, v100
	v_mfma_f32_32x32x16_bf16 v[16:31], v[74:77], v[16:19], 0
	v_mfma_f32_32x32x16_bf16 v[32:47], v[70:73], v[66:69], v[32:47]
	v_exp_f32_e32 v134, v101
	v_exp_f32_e32 v135, v102
	v_exp_f32_e32 v136, v103
	v_exp_f32_e32 v137, v104
	v_cvt_pk_bf16_f32 v70, v65, v131
	v_cvt_pk_bf16_f32 v71, v132, v133
	v_cvt_pk_bf16_f32 v72, v134, v135
	v_mfma_f32_32x32x16_bf16 v[16:31], v[78:81], v[66:69], v[16:31]
	v_cvt_pk_bf16_f32 v66, v106, v108
	v_cvt_pk_bf16_f32 v67, v109, v110
	v_cvt_pk_bf16_f32 v68, v111, v128
	v_cvt_pk_bf16_f32 v69, v129, v130
	v_cvt_pk_bf16_f32 v73, v136, v137
	ds_read_b128 v[74:77], v105 offset:27712
	ds_read_b128 v[78:81], v105 offset:27728
	ds_read_b128 v[98:101], v105 offset:32320
	ds_read_b128 v[102:105], v105 offset:32336
	s_waitcnt lgkmcnt(0)
	v_mfma_f32_32x32x16_bf16 v[48:63], v[82:85], v[66:69], v[48:63]
	v_mfma_f32_32x32x16_bf16 v[0:15], v[90:93], v[66:69], v[0:15]
	v_mfma_f32_32x32x16_bf16 v[48:63], v[86:89], v[70:73], v[48:63]
	v_mfma_f32_32x32x16_bf16 v[0:15], v[94:97], v[70:73], v[0:15]
	v_mfma_f32_32x32x16_bf16 v[32:47], v[74:77], v[66:69], v[32:47]
	v_mfma_f32_32x32x16_bf16 v[16:31], v[98:101], v[66:69], v[16:31]
	v_mfma_f32_32x32x16_bf16 v[32:47], v[78:81], v[70:73], v[32:47]
	v_mfma_f32_32x32x16_bf16 v[16:31], v[102:105], v[70:73], v[16:31]
	v_add_f32_e32 v66, 0, v106
	v_add_f32_e32 v66, v108, v66
	v_add_f32_e32 v66, v109, v66
	v_add_f32_e32 v66, v110, v66
	v_add_f32_e32 v66, v111, v66
	v_add_f32_e32 v66, v128, v66
	v_add_f32_e32 v66, v129, v66
	v_add_f32_e32 v66, v130, v66
	v_add_f32_e32 v65, v65, v66
	v_add_f32_e32 v65, v131, v65
	v_add_f32_e32 v65, v132, v65
	v_add_f32_e32 v65, v133, v65
	v_add_f32_e32 v65, v134, v65
	v_add_f32_e32 v65, v135, v65
	v_add_f32_e32 v65, v136, v65
	v_add_f32_e32 v65, v137, v65
	v_mov_b32_e32 v106, v177
	s_add_i32 s4, s20, s88
	s_waitcnt lgkmcnt(0)
	s_barrier
	v_pk_add_f32 v[156:157], v[64:65], v[106:107]
	v_add_u32_e32 v65, s4, v140
	v_sub_f32_e32 v64, v142, v156
	v_sub_u32_e32 v65, v146, v65
	v_add_u32_e32 v164, 64, v65
	s_mov_b32 s58, 0
	s_sub_i32 s91, 0, s4
	s_mov_b32 s8, 1
	s_mov_b32 s9, 0x9000
	s_mov_b64 s[10:11], s[46:47]
	s_mov_b64 s[76:77], s[40:41]
	s_mov_b32 s56, 0
	v_mov_b32_e32 v65, v64
	v_mov_b32_e32 v66, v64
	v_mov_b32_e32 v67, v64
	v_mov_b32_e32 v68, v64
	v_mov_b32_e32 v69, v64
	v_mov_b32_e32 v70, v64
	v_mov_b32_e32 v71, v64
	v_mov_b32_e32 v72, v64
	v_mov_b32_e32 v73, v64
	v_mov_b32_e32 v74, v64
	v_mov_b32_e32 v75, v64
	v_mov_b32_e32 v76, v64
	v_mov_b32_e32 v77, v64
	v_mov_b32_e32 v78, v64
	v_mov_b32_e32 v79, v64
	s_add_u32 s16, s10, 0xffffff80
	s_addc_u32 s17, s11, -1
	s_mov_b32 vcc_lo, 0x60000
	s_and_b64 s[4:5], s[52:53], exec
	s_cselect_b32 s80, s77, s17
	s_cselect_b32 s81, s76, s16
	s_cselect_b32 vcc_hi, 0x80, vcc_lo
	s_and_b64 s[4:5], s[48:49], exec
	s_cselect_b32 s80, s11, s80
	s_cselect_b32 s81, s10, s81
	s_cselect_b32 vcc_hi, vcc_lo, vcc_hi
	s_and_b64 s[4:5], s[36:37], exec
	s_cselect_b32 s5, s17, s80
	s_cselect_b32 s4, s16, s81
	s_cselect_b32 vcc_hi, vcc_lo, vcc_hi
	v_lshl_add_u64 v[240:241], s[4:5], 0, v[176:177]
	v_mov_b32_e32 v200, vcc_hi
	v_mov_b32_e32 v201, 0
	s_and_b64 s[4:5], s[28:29], exec
	s_cselect_b32 s80, s77, s17
	s_cselect_b32 s81, s76, s16
	s_cselect_b32 vcc_hi, 0x80, vcc_lo
	s_and_b64 s[4:5], s[66:67], exec
	s_cselect_b32 s80, s11, s80
	s_cselect_b32 s81, s10, s81
	s_cselect_b32 vcc_hi, vcc_lo, vcc_hi
	s_and_b64 s[4:5], s[50:51], exec
	s_cselect_b32 s5, s17, s80
	s_cselect_b32 s4, s16, s81
	s_cselect_b32 vcc_hi, vcc_lo, vcc_hi
	v_lshl_add_u64 v[242:243], s[4:5], 0, v[148:149]
	v_mov_b32_e32 v202, vcc_hi
	v_mov_b32_e32 v203, 0
	s_and_b64 s[4:5], s[60:61], exec
	s_cselect_b32 s80, s77, s17
	s_cselect_b32 s81, s76, s16
	s_cselect_b32 vcc_hi, 0x80, vcc_lo
	s_and_b64 s[4:5], s[38:39], exec
	s_cselect_b32 s80, s11, s80
	s_cselect_b32 s81, s10, s81
	s_cselect_b32 vcc_hi, vcc_lo, vcc_hi
	s_and_b64 s[4:5], s[62:63], exec
	s_cselect_b32 s5, s17, s80
	s_cselect_b32 s4, s16, s81
	s_cselect_b32 vcc_hi, vcc_lo, vcc_hi
	v_lshl_add_u64 v[244:245], s[4:5], 0, v[150:151]
	v_mov_b32_e32 v204, vcc_hi
	v_mov_b32_e32 v205, 0
	s_and_b64 s[4:5], s[6:7], exec
	s_cselect_b32 s80, s77, s17
	s_cselect_b32 s81, s76, s16
	s_cselect_b32 vcc_hi, 0x80, vcc_lo
	s_and_b64 s[4:5], s[12:13], exec
	s_cselect_b32 s80, s11, s80
	s_cselect_b32 s81, s10, s81
	s_cselect_b32 vcc_hi, vcc_lo, vcc_hi
	s_and_b64 s[4:5], s[22:23], exec
	s_cselect_b32 s5, s17, s80
	s_cselect_b32 s4, s16, s81
	s_cselect_b32 vcc_hi, vcc_lo, vcc_hi
	v_lshl_add_u64 v[246:247], s[4:5], 0, v[152:153]
	v_mov_b32_e32 v206, vcc_hi
	v_mov_b32_e32 v207, 0
	s_and_b64 s[4:5], s[14:15], exec
	s_cselect_b32 s80, s77, s17
	s_cselect_b32 s81, s76, s16
	s_cselect_b32 vcc_hi, 0x80, vcc_lo
	s_and_b64 s[4:5], s[0:1], exec
	s_cselect_b32 s80, s11, s80
	s_cselect_b32 s81, s10, s81
	s_cselect_b32 vcc_hi, vcc_lo, vcc_hi
	s_and_b64 s[4:5], s[68:69], exec
	s_cselect_b32 s5, s17, s80
	s_cselect_b32 s4, s16, s81
	s_cselect_b32 vcc_hi, vcc_lo, vcc_hi
	v_lshl_add_u64 v[248:249], s[4:5], 0, v[154:155]
	v_mov_b32_e32 v208, vcc_hi
	v_mov_b32_e32 v209, 0
	s_mov_b32 s32, 3
	s_setprio 1
	s_branch .LBB0_684

.LBB0_713:
	s_andn2_b64 vcc, exec, s[76:77]
	s_waitcnt vmcnt(0) lgkmcnt(0)
	s_barrier
	s_cbranch_vccnz .LBB0_656
	ds_read2st64_b32 v[66:67], v64 offset1:1
	ds_read2st64_b32 v[76:77], v64 offset0:2 offset1:3
	ds_read2st64_b32 v[78:79], v64 offset0:4 offset1:5
	ds_read2st64_b32 v[80:81], v64 offset0:6 offset1:7
	ds_read2st64_b32 v[82:83], v64 offset0:8 offset1:9
	ds_read2st64_b32 v[84:85], v64 offset0:10 offset1:11
	ds_read2st64_b32 v[86:87], v64 offset0:12 offset1:13
	ds_read2st64_b32 v[88:89], v64 offset0:14 offset1:15
	ds_read2st64_b32 v[90:91], v64 offset0:16 offset1:17
	ds_read2st64_b32 v[116:117], v64 offset0:18 offset1:19
	ds_read2st64_b32 v[118:119], v64 offset0:20 offset1:21
	ds_read2st64_b32 v[120:121], v64 offset0:22 offset1:23
	ds_read2st64_b32 v[122:123], v64 offset0:24 offset1:25
	ds_read2st64_b32 v[124:125], v64 offset0:26 offset1:27
	ds_read2st64_b32 v[126:127], v64 offset0:28 offset1:29
	ds_read2st64_b32 v[128:129], v64 offset0:30 offset1:31
	ds_read2st64_b32 v[130:131], v64 offset0:32 offset1:33
	ds_read2st64_b32 v[132:133], v64 offset0:34 offset1:35
	ds_read2st64_b32 v[134:135], v64 offset0:36 offset1:37
	ds_read2st64_b32 v[136:137], v64 offset0:38 offset1:39
	ds_read2st64_b32 v[138:139], v64 offset0:40 offset1:41
	ds_read2st64_b32 v[140:141], v64 offset0:42 offset1:43
	ds_read2st64_b32 v[142:143], v64 offset0:44 offset1:45
	ds_read2st64_b32 v[148:149], v64 offset0:46 offset1:47
	ds_read2st64_b32 v[68:69], v64 offset0:58 offset1:59
	ds_read2st64_b32 v[150:151], v64 offset0:48 offset1:49
	ds_read2st64_b32 v[152:153], v64 offset0:50 offset1:51
	ds_read2st64_b32 v[154:155], v64 offset0:52 offset1:53
	ds_read2st64_b32 v[156:157], v64 offset0:54 offset1:55
	ds_read2st64_b32 v[72:73], v64 offset0:60 offset1:61
	ds_read2st64_b32 v[96:97], v64 offset0:62 offset1:63
	ds_read2st64_b32 v[162:163], v64 offset0:56 offset1:57
	s_waitcnt lgkmcnt(14)
	v_pk_fma_f32 v[98:99], v[50:51], v[74:75], v[76:77] op_sel_hi:[1,0,1] neg_lo:[0,0,1] neg_hi:[0,0,1]
	v_pk_fma_f32 v[104:105], v[48:49], v[74:75], v[66:67] op_sel_hi:[1,0,1] neg_lo:[0,0,1] neg_hi:[0,0,1]
	global_load_dwordx4 v[64:67], v146, s[30:31]
	global_load_dwordx4 v[48:51], v146, s[30:31] offset:32
	v_pk_mul_f32 v[164:165], v[104:105], v[104:105]
	s_waitcnt lgkmcnt(7)
	v_pk_fma_f32 v[70:71], v[26:27], v[74:75], v[68:69] op_sel_hi:[1,0,1] neg_lo:[0,0,1] neg_hi:[0,0,1]
	s_waitcnt lgkmcnt(2)
	v_pk_fma_f32 v[68:69], v[28:29], v[74:75], v[72:73] op_sel_hi:[1,0,1] neg_lo:[0,0,1] neg_hi:[0,0,1]
	s_waitcnt lgkmcnt(1)
	v_pk_fma_f32 v[72:73], v[30:31], v[74:75], v[96:97] op_sel_hi:[1,0,1] neg_lo:[0,0,1] neg_hi:[0,0,1]
	v_or_b32_e32 v26, s34, v161
	v_pk_mul_f32 v[160:161], v[98:99], v[98:99]
	v_pk_fma_f32 v[102:103], v[54:55], v[74:75], v[80:81] op_sel_hi:[1,0,1] neg_lo:[0,0,1] neg_hi:[0,0,1]
	v_pk_fma_f32 v[108:109], v[52:53], v[74:75], v[78:79] op_sel_hi:[1,0,1] neg_lo:[0,0,1] neg_hi:[0,0,1]
	v_pk_fma_f32 v[106:107], v[58:59], v[74:75], v[84:85] op_sel_hi:[1,0,1] neg_lo:[0,0,1] neg_hi:[0,0,1]
	v_pk_fma_f32 v[112:113], v[56:57], v[74:75], v[82:83] op_sel_hi:[1,0,1] neg_lo:[0,0,1] neg_hi:[0,0,1]
	v_pk_fma_f32 v[110:111], v[62:63], v[74:75], v[88:89] op_sel_hi:[1,0,1] neg_lo:[0,0,1] neg_hi:[0,0,1]
	v_pk_fma_f32 v[114:115], v[60:61], v[74:75], v[86:87] op_sel_hi:[1,0,1] neg_lo:[0,0,1] neg_hi:[0,0,1]
	v_pk_fma_f32 v[60:61], v[2:3], v[74:75], v[116:117] op_sel_hi:[1,0,1] neg_lo:[0,0,1] neg_hi:[0,0,1]
	v_pk_fma_f32 v[62:63], v[0:1], v[74:75], v[90:91] op_sel_hi:[1,0,1] neg_lo:[0,0,1] neg_hi:[0,0,1]
	v_pk_fma_f32 v[76:77], v[6:7], v[74:75], v[120:121] op_sel_hi:[1,0,1] neg_lo:[0,0,1] neg_hi:[0,0,1]
	v_pk_fma_f32 v[80:81], v[4:5], v[74:75], v[118:119] op_sel_hi:[1,0,1] neg_lo:[0,0,1] neg_hi:[0,0,1]
	v_pk_fma_f32 v[78:79], v[10:11], v[74:75], v[124:125] op_sel_hi:[1,0,1] neg_lo:[0,0,1] neg_hi:[0,0,1]
	v_pk_fma_f32 v[82:83], v[8:9], v[74:75], v[122:123] op_sel_hi:[1,0,1] neg_lo:[0,0,1] neg_hi:[0,0,1]
	v_pk_fma_f32 v[84:85], v[14:15], v[74:75], v[128:129] op_sel_hi:[1,0,1] neg_lo:[0,0,1] neg_hi:[0,0,1]
	v_pk_fma_f32 v[86:87], v[12:13], v[74:75], v[126:127] op_sel_hi:[1,0,1] neg_lo:[0,0,1] neg_hi:[0,0,1]
	v_pk_fma_f32 v[34:35], v[34:35], v[74:75], v[132:133] op_sel_hi:[1,0,1] neg_lo:[0,0,1] neg_hi:[0,0,1]
	v_pk_fma_f32 v[88:89], v[32:33], v[74:75], v[130:131] op_sel_hi:[1,0,1] neg_lo:[0,0,1] neg_hi:[0,0,1]
	v_pk_fma_f32 v[38:39], v[38:39], v[74:75], v[136:137] op_sel_hi:[1,0,1] neg_lo:[0,0,1] neg_hi:[0,0,1]
	v_pk_fma_f32 v[90:91], v[36:37], v[74:75], v[134:135] op_sel_hi:[1,0,1] neg_lo:[0,0,1] neg_hi:[0,0,1]
	v_pk_fma_f32 v[36:37], v[42:43], v[74:75], v[140:141] op_sel_hi:[1,0,1] neg_lo:[0,0,1] neg_hi:[0,0,1]
	v_pk_fma_f32 v[42:43], v[40:41], v[74:75], v[138:139] op_sel_hi:[1,0,1] neg_lo:[0,0,1] neg_hi:[0,0,1]
	v_pk_fma_f32 v[40:41], v[46:47], v[74:75], v[148:149] op_sel_hi:[1,0,1] neg_lo:[0,0,1] neg_hi:[0,0,1]
	v_pk_fma_f32 v[44:45], v[44:45], v[74:75], v[142:143] op_sel_hi:[1,0,1] neg_lo:[0,0,1] neg_hi:[0,0,1]
	v_pk_fma_f32 v[18:19], v[18:19], v[74:75], v[152:153] op_sel_hi:[1,0,1] neg_lo:[0,0,1] neg_hi:[0,0,1]
	v_pk_fma_f32 v[46:47], v[16:17], v[74:75], v[150:151] op_sel_hi:[1,0,1] neg_lo:[0,0,1] neg_hi:[0,0,1]
	v_pk_fma_f32 v[16:17], v[22:23], v[74:75], v[156:157] op_sel_hi:[1,0,1] neg_lo:[0,0,1] neg_hi:[0,0,1]
	v_pk_fma_f32 v[20:21], v[20:21], v[74:75], v[154:155] op_sel_hi:[1,0,1] neg_lo:[0,0,1] neg_hi:[0,0,1]
	s_waitcnt lgkmcnt(0)
	v_pk_fma_f32 v[22:23], v[24:25], v[74:75], v[162:163] op_sel_hi:[1,0,1] neg_lo:[0,0,1] neg_hi:[0,0,1]
	v_add_f32_e32 v74, v164, v165
	v_add_f32_e32 v74, v74, v160
	v_pk_mul_f32 v[168:169], v[108:109], v[108:109]
	v_add_f32_e32 v74, v74, v161
	v_add_f32_e32 v74, v74, v168
	v_pk_mul_f32 v[166:167], v[102:103], v[102:103]
	v_add_f32_e32 v74, v74, v169
	global_load_dwordx4 v[56:59], v146, s[30:31] offset:64
	global_load_dwordx4 v[52:55], v146, s[30:31] offset:96
	v_add_f32_e32 v74, v74, v166
	v_pk_mul_f32 v[172:173], v[112:113], v[112:113]
	v_add_f32_e32 v74, v74, v167
	v_add_f32_e32 v74, v74, v172
	v_pk_mul_f32 v[170:171], v[106:107], v[106:107]
	v_add_f32_e32 v74, v74, v173
	v_add_f32_e32 v74, v74, v170
	v_pk_mul_f32 v[178:179], v[114:115], v[114:115]
	v_add_f32_e32 v74, v74, v171
	v_add_f32_e32 v74, v74, v178
	v_pk_mul_f32 v[174:175], v[110:111], v[110:111]
	v_add_f32_e32 v74, v74, v179
	v_add_f32_e32 v74, v74, v174
	v_pk_mul_f32 v[180:181], v[62:63], v[62:63]
	v_add_f32_e32 v74, v74, v175
	v_add_f32_e32 v74, v74, v180
	v_pk_mul_f32 v[116:117], v[60:61], v[60:61]
	v_add_f32_e32 v74, v74, v181
	v_add_f32_e32 v74, v74, v116
	v_pk_mul_f32 v[118:119], v[80:81], v[80:81]
	v_add_f32_e32 v74, v74, v117
	v_add_f32_e32 v74, v74, v118
	v_pk_mul_f32 v[120:121], v[76:77], v[76:77]
	v_add_f32_e32 v74, v74, v119
	v_add_f32_e32 v74, v74, v120
	v_pk_mul_f32 v[122:123], v[82:83], v[82:83]
	v_add_f32_e32 v74, v74, v121
	v_add_f32_e32 v74, v74, v122
	v_pk_mul_f32 v[124:125], v[78:79], v[78:79]
	v_add_f32_e32 v74, v74, v123
	v_add_f32_e32 v74, v74, v124
	v_pk_mul_f32 v[126:127], v[86:87], v[86:87]
	v_add_f32_e32 v74, v74, v125
	v_add_f32_e32 v74, v74, v126
	v_pk_mul_f32 v[128:129], v[84:85], v[84:85]
	v_add_f32_e32 v74, v74, v127
	v_add_f32_e32 v74, v74, v128
	v_pk_mul_f32 v[130:131], v[88:89], v[88:89]
	v_add_f32_e32 v74, v74, v129
	v_add_f32_e32 v74, v74, v130
	v_pk_mul_f32 v[132:133], v[34:35], v[34:35]
	v_add_f32_e32 v74, v74, v131
	v_add_f32_e32 v74, v74, v132
	v_pk_mul_f32 v[134:135], v[90:91], v[90:91]
	v_add_f32_e32 v74, v74, v133
	v_add_f32_e32 v74, v74, v134
	v_pk_mul_f32 v[136:137], v[38:39], v[38:39]
	v_add_f32_e32 v74, v74, v135
	v_add_f32_e32 v74, v74, v136
	v_pk_mul_f32 v[138:139], v[42:43], v[42:43]
	v_add_f32_e32 v74, v74, v137
	v_add_f32_e32 v74, v74, v138
	v_pk_mul_f32 v[140:141], v[36:37], v[36:37]
	v_add_f32_e32 v74, v74, v139
	v_add_f32_e32 v74, v74, v140
	v_pk_mul_f32 v[142:143], v[44:45], v[44:45]
	v_add_f32_e32 v74, v74, v141
	v_add_f32_e32 v74, v74, v142
	v_pk_mul_f32 v[148:149], v[40:41], v[40:41]
	v_add_f32_e32 v74, v74, v143
	v_add_f32_e32 v74, v74, v148
	v_pk_mul_f32 v[150:151], v[46:47], v[46:47]
	v_add_f32_e32 v74, v74, v149
	v_add_f32_e32 v74, v74, v150
	v_pk_mul_f32 v[152:153], v[18:19], v[18:19]
	v_add_f32_e32 v74, v74, v151
	v_add_f32_e32 v74, v74, v152
	v_pk_mul_f32 v[154:155], v[20:21], v[20:21]
	v_add_f32_e32 v74, v74, v153
	v_add_f32_e32 v74, v74, v154
	v_pk_mul_f32 v[156:157], v[16:17], v[16:17]
	v_add_f32_e32 v74, v74, v155
	v_ashrrev_i32_e32 v27, 31, v26
	v_readlane_b32 s0, v255, 20
	v_add_f32_e32 v74, v74, v156
	v_lshlrev_b64 v[26:27], 12, v[26:27]
	v_readlane_b32 s1, v255, 21
	v_pk_mul_f32 v[24:25], v[22:23], v[22:23]
	v_add_f32_e32 v74, v74, v157
	v_lshl_add_u64 v[26:27], s[0:1], 0, v[26:27]
	v_add_f32_e32 v24, v74, v24
	v_pk_mul_f32 v[92:93], v[70:71], v[70:71]
	v_lshl_add_u64 v[100:101], v[26:27], 0, s[72:73]
	global_load_dwordx4 v[26:29], v146, s[30:31] offset:128
	global_load_dwordx4 v[0:3], v146, s[30:31] offset:160
	v_add_f32_e32 v24, v24, v25
	v_add_f32_e32 v24, v24, v92
	v_pk_mul_f32 v[94:95], v[68:69], v[68:69]
	v_add_f32_e32 v24, v24, v93
	v_add_f32_e32 v24, v24, v94
	v_pk_mul_f32 v[96:97], v[72:73], v[72:73]
	v_add_f32_e32 v24, v24, v95
	v_add_f32_e32 v24, v24, v96
	v_add_f32_e32 v74, v24, v97
	ds_bpermute_b32 v75, v75, v74
	global_load_dwordx4 v[8:11], v146, s[30:31] offset:192
	global_load_dwordx4 v[4:7], v146, s[30:31] offset:224
	global_load_dwordx4 v[30:33], v146, s[30:31] offset:256
	global_load_dwordx4 v[12:15], v146, s[30:31] offset:288
	global_load_dwordx4 v[92:95], v146, s[30:31] offset:320
	global_load_dwordx4 v[116:119], v146, s[30:31] offset:352
	v_lshlrev_b32_e32 v176, 3, v158
	s_waitcnt lgkmcnt(0)
	v_add_f32_e32 v74, v74, v75
	v_fmamk_f32 v74, v74, 0x3c000000, v213
	v_rsq_f32_e32 v74, v74
	v_lshl_add_u64 v[24:25], v[100:101], 0, v[176:177]
	global_load_dwordx4 v[120:123], v146, s[30:31] offset:384
	global_load_dwordx4 v[124:127], v146, s[30:31] offset:416
	global_load_dwordx4 v[128:131], v146, s[30:31] offset:448
	v_mul_f32_e32 v74, v145, v74
	v_pk_mul_f32 v[96:97], v[104:105], v[74:75] op_sel_hi:[1,0]
	s_waitcnt vmcnt(14)
	v_pk_mul_f32 v[64:65], v[64:65], v[96:97]
	v_pk_mul_f32 v[96:97], v[98:99], v[74:75] op_sel_hi:[1,0]
	v_cvt_pk_bf16_f32 v64, v64, v65
	v_pk_mul_f32 v[66:67], v[66:67], v[96:97]
	s_nop 0
	v_cvt_pk_bf16_f32 v65, v66, v67
	global_store_dwordx2 v[24:25], v[64:65], off
	v_pk_mul_f32 v[64:65], v[108:109], v[74:75] op_sel_hi:[1,0]
	s_waitcnt vmcnt(14)
	v_pk_mul_f32 v[48:49], v[48:49], v[64:65]
	v_pk_mul_f32 v[64:65], v[102:103], v[74:75] op_sel_hi:[1,0]
	v_cvt_pk_bf16_f32 v48, v48, v49
	v_pk_mul_f32 v[50:51], v[50:51], v[64:65]
	s_nop 0
	v_cvt_pk_bf16_f32 v49, v50, v51
	global_store_dwordx2 v[24:25], v[48:49], off offset:16
	v_pk_mul_f32 v[48:49], v[112:113], v[74:75] op_sel_hi:[1,0]
	v_pk_mul_f32 v[50:51], v[106:107], v[74:75] op_sel_hi:[1,0]
	s_waitcnt vmcnt(14)
	v_pk_mul_f32 v[48:49], v[56:57], v[48:49]
	v_pk_mul_f32 v[50:51], v[58:59], v[50:51]
	v_cvt_pk_bf16_f32 v48, v48, v49
	v_cvt_pk_bf16_f32 v49, v50, v51
	global_store_dwordx2 v[24:25], v[48:49], off offset:32
	v_pk_mul_f32 v[48:49], v[114:115], v[74:75] op_sel_hi:[1,0]
	s_waitcnt vmcnt(14)
	v_pk_mul_f32 v[48:49], v[52:53], v[48:49]
	s_nop 0
	v_cvt_pk_bf16_f32 v52, v48, v49
	v_pk_mul_f32 v[48:49], v[110:111], v[74:75] op_sel_hi:[1,0]
	s_nop 0
	v_pk_mul_f32 v[48:49], v[54:55], v[48:49]
	s_nop 0
	v_cvt_pk_bf16_f32 v53, v48, v49
	global_load_dwordx4 v[48:51], v146, s[30:31] offset:480
	s_nop 0
	global_store_dwordx2 v[24:25], v[52:53], off offset:48
	v_pk_mul_f32 v[52:53], v[62:63], v[74:75] op_sel_hi:[1,0]
	s_waitcnt vmcnt(15)
	v_pk_mul_f32 v[26:27], v[52:53], v[26:27]
	v_pk_mul_f32 v[52:53], v[60:61], v[74:75] op_sel_hi:[1,0]
	v_cvt_pk_bf16_f32 v26, v26, v27
	v_pk_mul_f32 v[28:29], v[52:53], v[28:29]
	s_nop 0
	v_cvt_pk_bf16_f32 v27, v28, v29
	global_store_dwordx2 v[24:25], v[26:27], off offset:64
	v_pk_mul_f32 v[26:27], v[80:81], v[74:75] op_sel_hi:[1,0]
	s_waitcnt vmcnt(15)
	v_pk_mul_f32 v[0:1], v[26:27], v[0:1]
	v_pk_mul_f32 v[26:27], v[76:77], v[74:75] op_sel_hi:[1,0]
	v_cvt_pk_bf16_f32 v0, v0, v1
	v_pk_mul_f32 v[2:3], v[26:27], v[2:3]
	s_nop 0
	v_cvt_pk_bf16_f32 v1, v2, v3
	global_store_dwordx2 v[24:25], v[0:1], off offset:80
	v_pk_mul_f32 v[0:1], v[82:83], v[74:75] op_sel_hi:[1,0]
	v_pk_mul_f32 v[2:3], v[78:79], v[74:75] op_sel_hi:[1,0]
	s_waitcnt vmcnt(15)
	v_pk_mul_f32 v[0:1], v[0:1], v[8:9]
	v_pk_mul_f32 v[2:3], v[2:3], v[10:11]
	v_cvt_pk_bf16_f32 v0, v0, v1
	v_cvt_pk_bf16_f32 v1, v2, v3
	global_store_dwordx2 v[24:25], v[0:1], off offset:96
	v_pk_mul_f32 v[0:1], v[86:87], v[74:75] op_sel_hi:[1,0]
	v_pk_mul_f32 v[2:3], v[84:85], v[74:75] op_sel_hi:[1,0]
	s_waitcnt vmcnt(15)
	v_pk_mul_f32 v[0:1], v[0:1], v[4:5]
	v_pk_mul_f32 v[2:3], v[2:3], v[6:7]
	v_cvt_pk_bf16_f32 v0, v0, v1
	v_cvt_pk_bf16_f32 v1, v2, v3
	global_store_dwordx2 v[24:25], v[0:1], off offset:112
	v_pk_mul_f32 v[0:1], v[88:89], v[74:75] op_sel_hi:[1,0]
	v_pk_mul_f32 v[2:3], v[34:35], v[74:75] op_sel_hi:[1,0]
	s_waitcnt vmcnt(15)
	v_pk_mul_f32 v[0:1], v[0:1], v[30:31]
	v_pk_mul_f32 v[2:3], v[2:3], v[32:33]
	v_cvt_pk_bf16_f32 v0, v0, v1
	v_cvt_pk_bf16_f32 v1, v2, v3
	global_store_dwordx2 v[24:25], v[0:1], off offset:128
	v_pk_mul_f32 v[0:1], v[90:91], v[74:75] op_sel_hi:[1,0]
	v_pk_mul_f32 v[2:3], v[38:39], v[74:75] op_sel_hi:[1,0]
	s_waitcnt vmcnt(15)
	v_pk_mul_f32 v[0:1], v[0:1], v[12:13]
	v_pk_mul_f32 v[2:3], v[2:3], v[14:15]
	v_cvt_pk_bf16_f32 v0, v0, v1
	v_cvt_pk_bf16_f32 v1, v2, v3
	global_store_dwordx2 v[24:25], v[0:1], off offset:144
	v_pk_mul_f32 v[0:1], v[42:43], v[74:75] op_sel_hi:[1,0]
	v_pk_mul_f32 v[2:3], v[36:37], v[74:75] op_sel_hi:[1,0]
	s_waitcnt vmcnt(15)
	v_pk_mul_f32 v[0:1], v[0:1], v[92:93]
	v_pk_mul_f32 v[2:3], v[2:3], v[94:95]
	v_cvt_pk_bf16_f32 v0, v0, v1
	v_cvt_pk_bf16_f32 v1, v2, v3
	global_store_dwordx2 v[24:25], v[0:1], off offset:160
	v_pk_mul_f32 v[0:1], v[44:45], v[74:75] op_sel_hi:[1,0]
	v_pk_mul_f32 v[2:3], v[40:41], v[74:75] op_sel_hi:[1,0]
	s_waitcnt vmcnt(15)
	v_pk_mul_f32 v[0:1], v[0:1], v[116:117]
	v_pk_mul_f32 v[2:3], v[2:3], v[118:119]
	v_cvt_pk_bf16_f32 v0, v0, v1
	v_cvt_pk_bf16_f32 v1, v2, v3
	global_store_dwordx2 v[24:25], v[0:1], off offset:176
	v_pk_mul_f32 v[0:1], v[46:47], v[74:75] op_sel_hi:[1,0]
	v_pk_mul_f32 v[2:3], v[18:19], v[74:75] op_sel_hi:[1,0]
	s_waitcnt vmcnt(15)
	v_pk_mul_f32 v[0:1], v[0:1], v[120:121]
	v_pk_mul_f32 v[2:3], v[2:3], v[122:123]
	v_cvt_pk_bf16_f32 v0, v0, v1
	v_cvt_pk_bf16_f32 v1, v2, v3
	global_store_dwordx2 v[24:25], v[0:1], off offset:192
	v_pk_mul_f32 v[0:1], v[20:21], v[74:75] op_sel_hi:[1,0]
	v_pk_mul_f32 v[2:3], v[16:17], v[74:75] op_sel_hi:[1,0]
	s_waitcnt vmcnt(15)
	v_pk_mul_f32 v[0:1], v[0:1], v[124:125]
	v_pk_mul_f32 v[2:3], v[2:3], v[126:127]
	v_cvt_pk_bf16_f32 v0, v0, v1
	v_cvt_pk_bf16_f32 v1, v2, v3
	global_store_dwordx2 v[24:25], v[0:1], off offset:208
	v_pk_mul_f32 v[0:1], v[22:23], v[74:75] op_sel_hi:[1,0]
	v_pk_mul_f32 v[2:3], v[70:71], v[74:75] op_sel_hi:[1,0]
	s_waitcnt vmcnt(15)
	v_pk_mul_f32 v[0:1], v[0:1], v[128:129]
	v_pk_mul_f32 v[2:3], v[2:3], v[130:131]
	v_cvt_pk_bf16_f32 v0, v0, v1
	v_cvt_pk_bf16_f32 v1, v2, v3
	global_store_dwordx2 v[24:25], v[0:1], off offset:224
	v_pk_mul_f32 v[0:1], v[68:69], v[74:75] op_sel_hi:[1,0]
	v_pk_mul_f32 v[2:3], v[72:73], v[74:75] op_sel_hi:[1,0]
	s_waitcnt vmcnt(12)
	v_pk_mul_f32 v[0:1], v[0:1], v[48:49]
	v_pk_mul_f32 v[2:3], v[2:3], v[50:51]
	v_cvt_pk_bf16_f32 v0, v0, v1
	v_cvt_pk_bf16_f32 v1, v2, v3
	global_store_dwordx2 v[24:25], v[0:1], off offset:240
	s_branch .LBB0_656
	s_nop 0
	s_nop 0
	s_nop 0
	s_nop 0
	s_nop 0
	s_nop 0
.LBB0_715:
	s_cmpk_lg_i32 s8, 0x100
	s_mov_b64 s[0:1], -1
	s_cbranch_scc0 .LBB0_717
	s_abs_i32 s0, s8
	v_cvt_f32_u32_e32 v0, s0
	s_sub_i32 s4, 0, s0
	s_add_i32 s1, s8, 0x7f
	s_ashr_i32 s2, s1, 31
	v_rcp_iflag_f32_e32 v0, v0
	s_abs_i32 s1, s1
	s_ashr_i32 s3, s8, 31
	s_xor_b32 s2, s2, s3
	v_mul_f32_e32 v0, 0x4f7ffffe, v0
	v_cvt_u32_f32_e32 v0, v0
	s_nop 0
	v_readfirstlane_b32 s5, v0
	s_mul_i32 s4, s4, s5
	s_mul_hi_u32 s4, s5, s4
	s_add_i32 s5, s5, s4
	s_mul_hi_u32 s4, s1, s5
	s_mul_i32 s6, s4, s0
	s_sub_i32 s1, s1, s6
	s_add_i32 s7, s4, 1
	s_sub_i32 s6, s1, s0
	s_cmp_ge_u32 s1, s0
	s_cselect_b32 s4, s7, s4
	s_cselect_b32 s1, s6, s1
	s_add_i32 s6, s4, 1
	s_cmp_ge_u32 s1, s0
	s_cselect_b32 s1, s6, s4
	s_xor_b32 s1, s1, s2
	s_sub_i32 s1, s1, s2
	v_readlane_b32 s7, v255, 24
	s_mul_i32 s21, s1, s7
	s_sub_i32 s2, 0x80, s21
	s_min_i32 s1, s2, s1
	s_cmpk_lt_i32 s21, 0x80
	s_cselect_b32 s2, s1, 0
	s_add_i32 s1, s8, 0xff
	s_ashr_i32 s4, s1, 31
	s_abs_i32 s1, s1
	s_xor_b32 s3, s4, s3
	s_mul_hi_u32 s4, s1, s5
	s_mul_i32 s5, s4, s0
	s_sub_i32 s1, s1, s5
	s_add_i32 s5, s4, 1
	s_sub_i32 s6, s1, s0
	s_cmp_ge_u32 s1, s0
	s_cselect_b32 s4, s5, s4
	s_cselect_b32 s1, s6, s1
	s_add_i32 s5, s4, 1
	s_cmp_ge_u32 s1, s0
	s_cselect_b32 s0, s5, s4
	s_xor_b32 s0, s0, s3
	s_sub_i32 s0, s0, s3
	s_mul_i32 s3, s0, s7
	s_sub_i32 s1, 0x100, s3
	s_min_i32 s0, s1, s0
	s_cmpk_lt_i32 s3, 0x100
	s_cselect_b32 s20, s0, 0
	s_mov_b64 s[0:1], 0
